# v25 + phase0 row-reduce via permlane/DPP + redundant canonicalizing v_max removed in attention + top-k P prefetch
# baseline (speedup 1.0000x reference)
.LBB0_1076:
	s_nop 10
	v_max_f32_e32 v39, v2, v2
	v_max_f32_e32 v39, v18, v39
	v_max_f32_e32 v41, v3, v3
	v_max_f32_e32 v41, v19, v41
	v_max3_f32 v39, v39, s75, v41
	v_max_f32_e32 v41, v4, v4
	v_max_f32_e32 v41, v20, v41
	v_max_f32_e32 v43, v5, v5
	v_max_f32_e32 v43, v21, v43
	v_max3_f32 v39, v39, v41, v43
	v_max_f32_e32 v41, v6, v6
	v_max_f32_e32 v41, v22, v41
	v_max_f32_e32 v43, v7, v7
	v_max_f32_e32 v43, v23, v43
	v_max3_f32 v39, v39, v41, v43
	v_max_f32_e32 v41, v8, v8
	v_max_f32_e32 v41, v24, v41
	v_max_f32_e32 v43, v9, v9
	v_max_f32_e32 v43, v25, v43
	v_max3_f32 v39, v39, v41, v43
	v_max_f32_e32 v41, v10, v10
	v_max_f32_e32 v41, v26, v41
	v_max_f32_e32 v43, v11, v11
	v_max_f32_e32 v43, v27, v43
	v_max3_f32 v39, v39, v41, v43
	v_max_f32_e32 v41, v12, v12
	v_max_f32_e32 v41, v28, v41
	v_max_f32_e32 v43, v13, v13
	v_max_f32_e32 v43, v29, v43
	v_max3_f32 v39, v39, v41, v43
	v_max_f32_e32 v41, v14, v14
	v_max_f32_e32 v41, v30, v41
	v_max_f32_e32 v43, v15, v15
	v_max_f32_e32 v43, v31, v43
	v_max3_f32 v39, v39, v41, v43
	v_max_f32_e32 v41, v16, v16
	v_max_f32_e32 v41, v32, v41
	v_max_f32_e32 v43, v17, v17
	v_max_f32_e32 v44, v33, v33
	v_max_f32_e32 v43, v44, v43
	v_max3_f32 v41, v39, v41, v43
	s_branch .LBB0_1078

.LBB0_1081:
	s_nop 10
	v_max_f32_e32 v34, v130, v130
	v_max_f32_e32 v34, v146, v34
	v_max_f32_e32 v35, v131, v131
	v_max_f32_e32 v35, v147, v35
	v_max3_f32 v34, v41, v34, v35
	v_max_f32_e32 v35, v132, v132
	v_max_f32_e32 v35, v148, v35
	v_max_f32_e32 v41, v133, v133
	v_max_f32_e32 v41, v149, v41
	v_max3_f32 v34, v34, v35, v41
	v_max_f32_e32 v35, v134, v134
	v_max_f32_e32 v35, v150, v35
	v_max_f32_e32 v41, v135, v135
	v_max_f32_e32 v41, v151, v41
	v_max3_f32 v34, v34, v35, v41
	v_max_f32_e32 v35, v136, v136
	v_max_f32_e32 v35, v152, v35
	v_max_f32_e32 v41, v137, v137
	v_max_f32_e32 v41, v153, v41
	v_max3_f32 v34, v34, v35, v41
	v_max_f32_e32 v35, v138, v138
	v_max_f32_e32 v35, v154, v35
	v_max_f32_e32 v41, v139, v139
	v_max_f32_e32 v41, v155, v41
	v_max3_f32 v34, v34, v35, v41
	v_max_f32_e32 v35, v140, v140
	v_max_f32_e32 v35, v156, v35
	v_max_f32_e32 v41, v141, v141
	v_max_f32_e32 v41, v157, v41
	v_max3_f32 v34, v34, v35, v41
	v_max_f32_e32 v35, v142, v142
	v_max_f32_e32 v35, v158, v35
	v_max_f32_e32 v41, v143, v143
	v_max_f32_e32 v41, v159, v41
	v_max3_f32 v34, v34, v35, v41
	v_max_f32_e32 v35, v144, v144
	v_max_f32_e32 v35, v160, v35
	v_max_f32_e32 v41, v145, v145
	v_max_f32_e32 v42, v161, v161
	v_max_f32_e32 v41, v42, v41
	v_max3_f32 v41, v34, v35, v41
	s_cmp_gt_i32 s72, 1
	s_cselect_b64 s[10:11], -1, 0
	s_cmp_lt_i32 s72, 2
	s_cbranch_scc1 .LBB0_1087

.LBB0_1084:
	s_nop 10
	v_max_f32_e32 v34, v98, v98
	v_max_f32_e32 v34, v114, v34
	v_max_f32_e32 v35, v99, v99
	v_max_f32_e32 v35, v115, v35
	v_max3_f32 v34, v41, v34, v35
	v_max_f32_e32 v35, v100, v100
	v_max_f32_e32 v35, v116, v35
	v_max_f32_e32 v41, v101, v101
	v_max_f32_e32 v41, v117, v41
	v_max3_f32 v34, v34, v35, v41
	v_max_f32_e32 v35, v102, v102
	v_max_f32_e32 v35, v118, v35
	v_max_f32_e32 v41, v103, v103
	v_max_f32_e32 v41, v119, v41
	v_max3_f32 v34, v34, v35, v41
	v_max_f32_e32 v35, v104, v104
	v_max_f32_e32 v35, v120, v35
	v_max_f32_e32 v41, v105, v105
	v_max_f32_e32 v41, v121, v41
	v_max3_f32 v34, v34, v35, v41
	v_max_f32_e32 v35, v106, v106
	v_max_f32_e32 v35, v122, v35
	v_max_f32_e32 v41, v107, v107
	v_max_f32_e32 v41, v123, v41
	v_max3_f32 v34, v34, v35, v41
	v_max_f32_e32 v35, v108, v108
	v_max_f32_e32 v35, v124, v35
	v_max_f32_e32 v41, v109, v109
	v_max_f32_e32 v41, v125, v41
	v_max3_f32 v34, v34, v35, v41
	v_max_f32_e32 v35, v110, v110
	v_max_f32_e32 v35, v126, v35
	v_max_f32_e32 v41, v111, v111
	v_max_f32_e32 v41, v127, v41
	v_max3_f32 v34, v34, v35, v41
	v_max_f32_e32 v35, v112, v112
	v_max_f32_e32 v35, v128, v35
	v_max_f32_e32 v41, v113, v113
	v_max_f32_e32 v42, v129, v129
	v_max_f32_e32 v41, v42, v41
	v_max3_f32 v41, v34, v35, v41
	s_cmp_gt_i32 s72, 2
	s_cselect_b64 s[94:95], -1, 0
	s_cmp_lt_i32 s72, 3
	s_cbranch_scc0 .LBB0_1088

.LBB0_1090:
	s_nop 10
	v_max_f32_e32 v34, v66, v66
	v_max_f32_e32 v34, v82, v34
	v_max_f32_e32 v35, v67, v67
	v_max_f32_e32 v35, v83, v35
	v_max3_f32 v34, v41, v34, v35
	v_max_f32_e32 v35, v68, v68
	v_max_f32_e32 v35, v84, v35
	v_max_f32_e32 v40, v69, v69
	v_max_f32_e32 v40, v85, v40
	v_max3_f32 v34, v34, v35, v40
	v_max_f32_e32 v35, v70, v70
	v_max_f32_e32 v35, v86, v35
	v_max_f32_e32 v40, v71, v71
	v_max_f32_e32 v40, v87, v40
	v_max3_f32 v34, v34, v35, v40
	v_max_f32_e32 v35, v72, v72
	v_max_f32_e32 v35, v88, v35
	v_max_f32_e32 v40, v73, v73
	v_max_f32_e32 v40, v89, v40
	v_max3_f32 v34, v34, v35, v40
	v_max_f32_e32 v35, v74, v74
	v_max_f32_e32 v35, v90, v35
	v_max_f32_e32 v40, v75, v75
	v_max_f32_e32 v40, v91, v40
	v_max3_f32 v34, v34, v35, v40
	v_max_f32_e32 v35, v76, v76
	v_max_f32_e32 v35, v92, v35
	v_max_f32_e32 v40, v77, v77
	v_max_f32_e32 v40, v93, v40
	v_max3_f32 v34, v34, v35, v40
	v_max_f32_e32 v35, v78, v78
	v_max_f32_e32 v35, v94, v35
	v_max_f32_e32 v40, v79, v79
	v_max_f32_e32 v40, v95, v40
	v_max3_f32 v34, v34, v35, v40
	v_max_f32_e32 v35, v80, v80
	v_max_f32_e32 v35, v96, v35
	v_max_f32_e32 v40, v81, v81
	v_max_f32_e32 v40, v97, v40
	v_max3_f32 v41, v34, v35, v40

.LBB0_1139:
	v_cmp_eq_u32_e64 s[4:5], 0, v227
	v_cmp_eq_u32_e64 s[6:7], s68, v227
	s_or_b64 s[8:9], s[4:5], s[6:7]
	s_sub_i32 s6, 62, s74
	s_lshl_b32 s0, s72, 6
	v_cmp_eq_u32_e64 s[6:7], s6, v227
	v_lshlrev_b32_e32 v34, 4, v227
	s_add_i32 s0, s0, 64
	v_lshlrev_b32_e32 v38, 2, v227
	s_or_b64 s[6:7], s[8:9], s[6:7]
	s_movk_i32 s8, 0xff00
	v_lshl_add_u32 v42, v225, 8, 0
	v_lshl_or_b32 v44, v225, 13, v34
	v_cmp_gt_i32_e32 vcc, s0, v38
	v_xor_b32_e32 v39, 63, v227
	v_xor_b32_e32 v40, 0x7f, v227
	v_cmp_lt_i32_e64 s[0:1], s68, v227
	v_cmp_ne_u32_e64 s[2:3], 0, v227
	v_bitop3_b32 v41, v227, s8, 63 bitop3:0xde
	s_mov_b32 s12, 8
	v_add_u32_e32 v43, v42, v38
	v_add_u32_e32 v45, 0x10000, v44
	v_lshl_add_u32 v46, v225, 6, v197
	s_barrier
	ds_read_b128 v[128:131], v45
	ds_read_b32 v132, v44 offset:65532
	s_branch .LBB0_1141

.LBB0_1141:
	s_waitcnt lgkmcnt(0)
	v_add_f32_e32 v34, v128, v129
	v_add_f32_e32 v34, v34, v130
	v_fma_f32 v37, 2.0, v34, v131
	v_cndmask_b32_e64 v34, 0, v132, s[2:3]
	v_add_f32_e32 v37, v37, v34
	v_and_b32_e32 v34, 0xffffffc0, v37
	v_add_u32_e32 v34, v34, v40
	v_cndmask_b32_e64 v34, v34, v39, s[0:1]
	v_cndmask_b32_e64 v47, v34, v41, s[6:7]
	ds_write_b32 v43, v47
	ds_read_b128 v[60:63], v42
	ds_read_b128 v[64:67], v42 offset:16
	ds_read_b128 v[68:71], v42 offset:32
	ds_read_b128 v[72:75], v42 offset:48
	ds_read_b128 v[76:79], v42 offset:64
	ds_read_b128 v[80:83], v42 offset:80
	ds_read_b128 v[84:87], v42 offset:96
	ds_read_b128 v[88:91], v42 offset:112
	v_mov_b32_e32 v34, 0
	v_mov_b32_e32 v35, 0
	v_add_u32_e32 v133, 0x400, v44
	s_waitcnt lgkmcnt(7)
	ds_read_b128 v[92:95], v42 offset:128
	ds_read_b128 v[96:99], v42 offset:144
	ds_read_b128 v[100:103], v42 offset:160
	ds_read_b128 v[104:107], v42 offset:176
	ds_read_b128 v[108:111], v42 offset:192
	ds_read_b128 v[112:115], v42 offset:208
	ds_read_b128 v[120:123], v42 offset:224
	ds_read_b128 v[124:127], v42 offset:240
	v_cmp_gt_u32_e64 s[14:15], v60, v47
	v_cmp_gt_u32_e64 s[8:9], v61, v47
	v_cmp_gt_u32_e64 s[10:11], v62, v47
	v_addc_co_u32_e64 v34, s[14:15], 0, v34, s[14:15]
	v_cmp_gt_u32_e64 s[14:15], v63, v47
	v_addc_co_u32_e64 v35, s[8:9], 0, v35, s[8:9]
	s_waitcnt lgkmcnt(14)
	v_cmp_gt_u32_e64 s[8:9], v64, v47
	v_addc_co_u32_e64 v34, s[10:11], 0, v34, s[10:11]
	v_cmp_gt_u32_e64 s[10:11], v65, v47
	v_addc_co_u32_e64 v35, s[14:15], 0, v35, s[14:15]
	v_cmp_gt_u32_e64 s[14:15], v66, v47
	v_addc_co_u32_e64 v34, s[8:9], 0, v34, s[8:9]
	v_cmp_gt_u32_e64 s[8:9], v67, v47
	v_addc_co_u32_e64 v35, s[10:11], 0, v35, s[10:11]
	s_waitcnt lgkmcnt(13)
	v_cmp_gt_u32_e64 s[10:11], v68, v47
	v_addc_co_u32_e64 v34, s[14:15], 0, v34, s[14:15]
	v_cmp_gt_u32_e64 s[14:15], v69, v47
	v_addc_co_u32_e64 v35, s[8:9], 0, v35, s[8:9]
	v_cmp_gt_u32_e64 s[8:9], v70, v47
	v_addc_co_u32_e64 v34, s[10:11], 0, v34, s[10:11]
	v_cmp_gt_u32_e64 s[10:11], v71, v47
	v_addc_co_u32_e64 v35, s[14:15], 0, v35, s[14:15]
	s_waitcnt lgkmcnt(12)
	ds_read_b128 v[128:131], v45 offset:1024
	ds_read_b32 v132, v133 offset:65532
	v_cmp_gt_u32_e64 s[14:15], v72, v47
	v_addc_co_u32_e64 v34, s[8:9], 0, v34, s[8:9]
	v_cmp_gt_u32_e64 s[8:9], v73, v47
	v_addc_co_u32_e64 v35, s[10:11], 0, v35, s[10:11]
	v_cmp_gt_u32_e64 s[10:11], v74, v47
	v_addc_co_u32_e64 v34, s[14:15], 0, v34, s[14:15]
	v_cmp_gt_u32_e64 s[14:15], v75, v47
	v_addc_co_u32_e64 v35, s[8:9], 0, v35, s[8:9]
	s_waitcnt lgkmcnt(13)
	v_cmp_gt_u32_e64 s[8:9], v76, v47
	v_addc_co_u32_e64 v34, s[10:11], 0, v34, s[10:11]
	v_cmp_gt_u32_e64 s[10:11], v77, v47
	v_addc_co_u32_e64 v35, s[14:15], 0, v35, s[14:15]
	v_cmp_gt_u32_e64 s[14:15], v78, v47
	v_addc_co_u32_e64 v34, s[8:9], 0, v34, s[8:9]
	v_cmp_gt_u32_e64 s[8:9], v79, v47
	v_addc_co_u32_e64 v35, s[10:11], 0, v35, s[10:11]
	s_waitcnt lgkmcnt(12)
	v_cmp_gt_u32_e64 s[10:11], v80, v47
	v_addc_co_u32_e64 v34, s[14:15], 0, v34, s[14:15]
	v_cmp_gt_u32_e64 s[14:15], v81, v47
	v_addc_co_u32_e64 v35, s[8:9], 0, v35, s[8:9]
	v_cmp_gt_u32_e64 s[8:9], v82, v47
	v_addc_co_u32_e64 v34, s[10:11], 0, v34, s[10:11]
	v_cmp_gt_u32_e64 s[10:11], v83, v47
	v_addc_co_u32_e64 v35, s[14:15], 0, v35, s[14:15]
	s_waitcnt lgkmcnt(11)
	v_cmp_gt_u32_e64 s[14:15], v84, v47
	v_addc_co_u32_e64 v34, s[8:9], 0, v34, s[8:9]
	v_cmp_gt_u32_e64 s[8:9], v85, v47
	v_addc_co_u32_e64 v35, s[10:11], 0, v35, s[10:11]
	v_cmp_gt_u32_e64 s[10:11], v86, v47
	v_addc_co_u32_e64 v34, s[14:15], 0, v34, s[14:15]
	v_cmp_gt_u32_e64 s[14:15], v87, v47
	v_addc_co_u32_e64 v35, s[8:9], 0, v35, s[8:9]
	s_waitcnt lgkmcnt(10)
	v_cmp_gt_u32_e64 s[8:9], v88, v47
	v_addc_co_u32_e64 v34, s[10:11], 0, v34, s[10:11]
	v_cmp_gt_u32_e64 s[10:11], v89, v47
	v_addc_co_u32_e64 v35, s[14:15], 0, v35, s[14:15]
	v_cmp_gt_u32_e64 s[14:15], v90, v47
	v_addc_co_u32_e64 v34, s[8:9], 0, v34, s[8:9]
	v_cmp_gt_u32_e64 s[8:9], v91, v47
	v_addc_co_u32_e64 v35, s[10:11], 0, v35, s[10:11]
	s_waitcnt lgkmcnt(9)
	v_cmp_gt_u32_e64 s[10:11], v92, v47
	v_addc_co_u32_e64 v34, s[14:15], 0, v34, s[14:15]
	v_cmp_gt_u32_e64 s[14:15], v93, v47
	v_addc_co_u32_e64 v35, s[8:9], 0, v35, s[8:9]
	v_cmp_gt_u32_e64 s[8:9], v94, v47
	v_addc_co_u32_e64 v34, s[10:11], 0, v34, s[10:11]
	v_cmp_gt_u32_e64 s[10:11], v95, v47
	v_addc_co_u32_e64 v35, s[14:15], 0, v35, s[14:15]
	s_waitcnt lgkmcnt(8)
	v_cmp_gt_u32_e64 s[14:15], v96, v47
	v_addc_co_u32_e64 v34, s[8:9], 0, v34, s[8:9]
	v_cmp_gt_u32_e64 s[8:9], v97, v47
	v_addc_co_u32_e64 v35, s[10:11], 0, v35, s[10:11]
	v_cmp_gt_u32_e64 s[10:11], v98, v47
	v_addc_co_u32_e64 v34, s[14:15], 0, v34, s[14:15]
	v_cmp_gt_u32_e64 s[14:15], v99, v47
	v_addc_co_u32_e64 v35, s[8:9], 0, v35, s[8:9]
	s_waitcnt lgkmcnt(7)
	v_cmp_gt_u32_e64 s[8:9], v100, v47
	v_addc_co_u32_e64 v34, s[10:11], 0, v34, s[10:11]
	v_cmp_gt_u32_e64 s[10:11], v101, v47
	v_addc_co_u32_e64 v35, s[14:15], 0, v35, s[14:15]
	v_cmp_gt_u32_e64 s[14:15], v102, v47
	v_addc_co_u32_e64 v34, s[8:9], 0, v34, s[8:9]
	v_cmp_gt_u32_e64 s[8:9], v103, v47
	v_addc_co_u32_e64 v35, s[10:11], 0, v35, s[10:11]
	s_waitcnt lgkmcnt(6)
	v_cmp_gt_u32_e64 s[10:11], v104, v47
	v_addc_co_u32_e64 v34, s[14:15], 0, v34, s[14:15]
	v_cmp_gt_u32_e64 s[14:15], v105, v47
	v_addc_co_u32_e64 v35, s[8:9], 0, v35, s[8:9]
	v_cmp_gt_u32_e64 s[8:9], v106, v47
	v_addc_co_u32_e64 v34, s[10:11], 0, v34, s[10:11]
	v_cmp_gt_u32_e64 s[10:11], v107, v47
	v_addc_co_u32_e64 v35, s[14:15], 0, v35, s[14:15]
	s_waitcnt lgkmcnt(5)
	v_cmp_gt_u32_e64 s[14:15], v108, v47
	v_addc_co_u32_e64 v34, s[8:9], 0, v34, s[8:9]
	v_cmp_gt_u32_e64 s[8:9], v109, v47
	v_addc_co_u32_e64 v35, s[10:11], 0, v35, s[10:11]
	v_cmp_gt_u32_e64 s[10:11], v110, v47
	v_addc_co_u32_e64 v34, s[14:15], 0, v34, s[14:15]
	v_cmp_gt_u32_e64 s[14:15], v111, v47
	v_addc_co_u32_e64 v35, s[8:9], 0, v35, s[8:9]
	s_waitcnt lgkmcnt(4)
	v_cmp_gt_u32_e64 s[8:9], v112, v47
	v_addc_co_u32_e64 v34, s[10:11], 0, v34, s[10:11]
	v_cmp_gt_u32_e64 s[10:11], v113, v47
	v_addc_co_u32_e64 v35, s[14:15], 0, v35, s[14:15]
	v_cmp_gt_u32_e64 s[14:15], v114, v47
	v_addc_co_u32_e64 v34, s[8:9], 0, v34, s[8:9]
	v_cmp_gt_u32_e64 s[8:9], v115, v47
	v_addc_co_u32_e64 v35, s[10:11], 0, v35, s[10:11]
	s_waitcnt lgkmcnt(3)
	v_cmp_gt_u32_e64 s[10:11], v120, v47
	v_addc_co_u32_e64 v34, s[14:15], 0, v34, s[14:15]
	v_cmp_gt_u32_e64 s[14:15], v121, v47
	v_addc_co_u32_e64 v35, s[8:9], 0, v35, s[8:9]
	v_cmp_gt_u32_e64 s[8:9], v122, v47
	v_addc_co_u32_e64 v34, s[10:11], 0, v34, s[10:11]
	v_cmp_gt_u32_e64 s[10:11], v123, v47
	v_addc_co_u32_e64 v35, s[14:15], 0, v35, s[14:15]
	s_waitcnt lgkmcnt(2)
	v_cmp_gt_u32_e64 s[14:15], v124, v47
	v_addc_co_u32_e64 v34, s[8:9], 0, v34, s[8:9]
	v_cmp_gt_u32_e64 s[8:9], v125, v47
	v_addc_co_u32_e64 v35, s[10:11], 0, v35, s[10:11]
	v_cmp_gt_u32_e64 s[10:11], v126, v47
	v_addc_co_u32_e64 v34, s[14:15], 0, v34, s[14:15]
	v_cmp_gt_u32_e64 s[14:15], v127, v47
	v_addc_co_u32_e64 v35, s[8:9], 0, v35, s[8:9]
	v_addc_co_u32_e64 v34, s[10:11], 0, v34, s[10:11]
	v_addc_co_u32_e64 v35, s[14:15], 0, v35, s[14:15]
	v_add_u32_e32 v34, v34, v35
	v_cmp_gt_u32_e64 s[10:11], 16, v34
	s_and_saveexec_b64 s[8:9], s[4:5]
	s_cbranch_execz .LBB0_1140
	v_add_u32_e32 v34, 0, v46
	v_mov_b64_e32 v[36:37], s[10:11]
	ds_write_b64 v34, v[36:37]
	s_branch .LBB0_1140

.LBB0_1158:
	v_max3_f32 v108, v34, v35, v36
	v_max3_f32 v108, v108, v37, v38
	v_max3_f32 v108, v108, v39, v40
	v_max3_f32 v108, v108, v41, v42
	v_max3_f32 v108, v108, v43, v44
	v_max3_f32 v108, v108, v45, v46
	v_max3_f32 v108, v108, v47, v48
	v_max3_f32 v108, v108, v49, v50
	v_max3_f32 v108, v108, v51, v52
	v_max3_f32 v108, v108, v53, v54
	v_max3_f32 v108, v108, v55, v56
	v_max3_f32 v108, v108, v57, v58
	v_max3_f32 v108, v108, v59, v60
	v_max3_f32 v108, v108, v61, v62
	v_max3_f32 v108, v108, v63, v64
	v_max_f32_e32 v108, v108, v65
	ds_bpermute_b32 v110, v209, v108
	v_sub_co_u32_e64 v111, vcc, s42, 32
	v_lshrrev_b32_e32 v0, s42, v102
	v_lshrrev_b32_e32 v111, v111, v103
	v_cndmask_b32_e32 v0, v111, v0, vcc
	v_and_b32_e32 v0, 1, v0
	s_waitcnt lgkmcnt(0)
	v_max_f32_e32 v110, v110, v110
	v_max_f32_e32 v108, v108, v110
	v_cmp_eq_u32_e64 s[2:3], 0, v0
	s_nop 1
	v_cndmask_b32_e64 v0, v108, v196, s[2:3]
	v_max_f32_e32 v117, v116, v0
	v_sub_f32_e32 v0, v116, v117
	v_exp_f32_e32 v108, v0
	s_nop 0
	v_cmp_neq_f32_e32 vcc, 1.0, v108
	s_cbranch_vccz .LBB0_1160
	v_pk_mul_f32 v[32:33], v[32:33], v[108:109] op_sel_hi:[1,0]
	v_pk_mul_f32 v[30:31], v[30:31], v[108:109] op_sel_hi:[1,0]
	v_pk_mul_f32 v[28:29], v[28:29], v[108:109] op_sel_hi:[1,0]
	v_pk_mul_f32 v[26:27], v[26:27], v[108:109] op_sel_hi:[1,0]
	v_pk_mul_f32 v[24:25], v[24:25], v[108:109] op_sel_hi:[1,0]
	v_pk_mul_f32 v[22:23], v[22:23], v[108:109] op_sel_hi:[1,0]
	v_pk_mul_f32 v[20:21], v[20:21], v[108:109] op_sel_hi:[1,0]
	v_pk_mul_f32 v[18:19], v[18:19], v[108:109] op_sel_hi:[1,0]
	v_pk_mul_f32 v[16:17], v[16:17], v[108:109] op_sel_hi:[1,0]
	v_pk_mul_f32 v[14:15], v[14:15], v[108:109] op_sel_hi:[1,0]
	v_pk_mul_f32 v[12:13], v[12:13], v[108:109] op_sel_hi:[1,0]
	v_pk_mul_f32 v[10:11], v[10:11], v[108:109] op_sel_hi:[1,0]
	v_pk_mul_f32 v[8:9], v[8:9], v[108:109] op_sel_hi:[1,0]
	v_pk_mul_f32 v[6:7], v[6:7], v[108:109] op_sel_hi:[1,0]
	v_pk_mul_f32 v[4:5], v[4:5], v[108:109] op_sel_hi:[1,0]
	v_pk_mul_f32 v[2:3], v[2:3], v[108:109] op_sel_hi:[1,0]
.LBB0_1160:
	v_max_f32_e32 v0, 0xefa18f08, v117
	v_cndmask_b32_e64 v116, v0, v198, s[2:3]
	v_sub_f32_e32 v0, v34, v116
	v_exp_f32_e32 v34, v0
	v_sub_f32_e32 v0, v50, v116
	v_exp_f32_e32 v50, v0
	v_sub_f32_e32 v0, v35, v116
	v_exp_f32_e32 v154, v0
	v_sub_f32_e32 v0, v51, v116
	v_exp_f32_e32 v0, v0
	v_sub_f32_e32 v35, v36, v116
	v_add_f32_e32 v155, v34, v50
	v_exp_f32_e32 v36, v35
	v_sub_f32_e32 v35, v52, v116
	v_pk_add_f32 v[110:111], v[154:155], v[0:1]
	v_exp_f32_e32 v52, v35
	v_sub_f32_e32 v35, v37, v116
	v_pk_add_f32 v[110:111], v[110:111], v[110:111] op_sel_hi:[0,1]
	v_exp_f32_e32 v156, v35
	v_sub_f32_e32 v35, v53, v116
	v_exp_f32_e32 v110, v35
	v_sub_f32_e32 v37, v38, v116
	v_add_f32_e32 v157, v36, v52
	v_exp_f32_e32 v38, v37
	v_sub_f32_e32 v37, v54, v116
	v_pk_add_f32 v[118:119], v[156:157], v[110:111]
	v_exp_f32_e32 v54, v37
	v_sub_f32_e32 v37, v39, v116
	v_pk_add_f32 v[158:159], v[118:119], v[118:119] op_sel_hi:[0,1]
	v_exp_f32_e32 v160, v37
	v_sub_f32_e32 v37, v55, v116
	v_exp_f32_e32 v158, v37
	v_sub_f32_e32 v37, v40, v116
	v_add_f32_e32 v161, v38, v54
	v_exp_f32_e32 v40, v37
	v_sub_f32_e32 v37, v56, v116
	v_pk_add_f32 v[126:127], v[160:161], v[158:159]
	v_exp_f32_e32 v56, v37
	v_sub_f32_e32 v37, v41, v116
	v_pk_add_f32 v[186:187], v[126:127], v[126:127] op_sel_hi:[0,1]
	v_exp_f32_e32 v188, v37
	v_sub_f32_e32 v37, v57, v116
	v_exp_f32_e32 v186, v37
	v_sub_f32_e32 v37, v42, v116
	v_add_f32_e32 v189, v40, v56
	v_exp_f32_e32 v42, v37
	v_sub_f32_e32 v37, v58, v116
	v_pk_add_f32 v[134:135], v[188:189], v[186:187]
	v_exp_f32_e32 v58, v37
	v_sub_f32_e32 v37, v43, v116
	v_pk_add_f32 v[190:191], v[134:135], v[134:135] op_sel_hi:[0,1]
	v_exp_f32_e32 v192, v37
	v_sub_f32_e32 v37, v59, v116
	v_exp_f32_e32 v190, v37
	v_sub_f32_e32 v37, v44, v116
	v_add_f32_e32 v193, v42, v58
	v_exp_f32_e32 v44, v37
	v_sub_f32_e32 v37, v60, v116
	v_pk_add_f32 v[142:143], v[192:193], v[190:191]
	v_exp_f32_e32 v60, v37
	v_sub_f32_e32 v37, v45, v116
	v_pk_add_f32 v[194:195], v[142:143], v[142:143] op_sel_hi:[0,1]
	v_exp_f32_e32 v224, v37
	v_sub_f32_e32 v37, v61, v116
	v_exp_f32_e32 v194, v37
	v_lshl_add_u32 v35, s45, 14, v112
	ds_read_b64_tr_b16 v[118:119], v35 offset:8192
	ds_read_b64_tr_b16 v[120:121], v35 offset:8704
	ds_read_b64_tr_b16 v[122:123], v35 offset:9216
	ds_read_b64_tr_b16 v[124:125], v35 offset:9728
	ds_read_b64_tr_b16 v[126:127], v35 offset:12288
	ds_read_b64_tr_b16 v[128:129], v35 offset:12800
	ds_read_b64_tr_b16 v[130:131], v35 offset:13312
	ds_read_b64_tr_b16 v[132:133], v35 offset:13824
	ds_read_b64_tr_b16 v[134:135], v35 offset:10240
	ds_read_b64_tr_b16 v[136:137], v35 offset:10752
	ds_read_b64_tr_b16 v[138:139], v35 offset:11264
	ds_read_b64_tr_b16 v[140:141], v35 offset:11776
	ds_read_b64_tr_b16 v[142:143], v35 offset:14336
	ds_read_b64_tr_b16 v[144:145], v35 offset:14848
	ds_read_b64_tr_b16 v[146:147], v35 offset:15360
	ds_read_b64_tr_b16 v[148:149], v35 offset:15872
	v_add_f32_e32 v225, v44, v60
	v_sub_f32_e32 v35, v46, v116
	v_pk_add_f32 v[150:151], v[224:225], v[194:195]
	v_exp_f32_e32 v46, v35
	v_sub_f32_e32 v35, v62, v116
	v_pk_add_f32 v[226:227], v[150:151], v[150:151] op_sel_hi:[0,1]
	v_cvt_pk_bf16_f32 v150, v34, v154
	v_cvt_pk_bf16_f32 v151, v36, v156
	v_cvt_pk_bf16_f32 v152, v38, v160
	v_cvt_pk_bf16_f32 v153, v40, v188
	v_exp_f32_e32 v62, v35
	v_sub_f32_e32 v35, v47, v116
	s_waitcnt lgkmcnt(0)
	v_mfma_f32_32x32x16_bf16 v[2:17], v[118:121], v[150:153], v[2:17]
	v_exp_f32_e32 v228, v35
	v_sub_f32_e32 v35, v63, v116
	v_exp_f32_e32 v226, v35
	v_sub_f32_e32 v35, v48, v116
	v_exp_f32_e32 v48, v35
	v_sub_f32_e32 v35, v49, v116
	v_exp_f32_e32 v49, v35
	v_mfma_f32_32x32x16_bf16 v[18:33], v[126:129], v[150:153], v[18:33]
	v_cvt_pk_bf16_f32 v118, v42, v192
	v_cvt_pk_bf16_f32 v119, v44, v224
	v_cvt_pk_bf16_f32 v120, v46, v228
	v_cvt_pk_bf16_f32 v121, v48, v49
	v_sub_f32_e32 v35, v64, v116
	v_exp_f32_e32 v64, v35
	v_sub_f32_e32 v35, v65, v116
	v_mfma_f32_32x32x16_bf16 v[2:17], v[122:125], v[118:121], v[2:17]
	v_exp_f32_e32 v65, v35
	v_add_f32_e32 v229, v46, v62
	v_pk_add_f32 v[122:123], v[228:229], v[226:227]
	v_add_f32_e32 v111, v48, v64
	v_pk_add_f32 v[122:123], v[122:123], v[122:123] op_sel_hi:[0,1]
	v_mov_b32_e32 v122, v65
	v_mfma_f32_32x32x16_bf16 v[18:33], v[130:133], v[118:121], v[18:33]
	v_cvt_pk_bf16_f32 v118, v50, v0
	v_cvt_pk_bf16_f32 v119, v52, v110
	v_cvt_pk_bf16_f32 v120, v54, v158
	v_cvt_pk_bf16_f32 v121, v56, v186
	v_mov_b32_e32 v110, v49
	v_pk_add_f32 v[110:111], v[110:111], v[122:123]
	v_mfma_f32_32x32x16_bf16 v[2:17], v[134:137], v[118:121], v[2:17]
	v_add_f32_e32 v0, v110, v111
	v_fmac_f32_e32 v0, v115, v108
	v_mfma_f32_32x32x16_bf16 v[18:33], v[142:145], v[118:121], v[18:33]
	v_cvt_pk_bf16_f32 v118, v58, v190
	v_cvt_pk_bf16_f32 v119, v60, v194
	v_cvt_pk_bf16_f32 v120, v62, v226
	v_cvt_pk_bf16_f32 v121, v64, v65
	s_nop 1
	v_mfma_f32_32x32x16_bf16 v[2:17], v[138:141], v[118:121], v[2:17]
	v_mov_b32_e32 v115, v0
	v_mfma_f32_32x32x16_bf16 v[18:33], v[146:149], v[118:121], v[18:33]
	s_branch .LBB0_1162

.LBB0_1171:
	v_max3_f32 v108, v66, v67, v68
	v_max3_f32 v108, v108, v69, v70
	v_max3_f32 v108, v108, v71, v72
	v_max3_f32 v108, v108, v73, v74
	v_max3_f32 v108, v108, v75, v76
	v_max3_f32 v108, v108, v77, v78
	v_max3_f32 v108, v108, v79, v80
	v_max3_f32 v108, v108, v81, v82
	v_max3_f32 v108, v108, v83, v84
	v_max3_f32 v108, v108, v85, v86
	v_max3_f32 v108, v108, v87, v88
	v_max3_f32 v108, v108, v89, v90
	v_max3_f32 v108, v108, v91, v92
	v_max3_f32 v108, v108, v93, v94
	v_max3_f32 v108, v108, v95, v96
	v_max_f32_e32 v108, v108, v97
	ds_bpermute_b32 v110, v209, v108
	s_cmp_lt_u32 s42, 32
	s_cselect_b64 vcc, -1, 0
	s_sub_i32 s2, s42, 31
	v_lshrrev_b32_e32 v0, s40, v102
	v_lshrrev_b32_e32 v111, s2, v103
	v_cndmask_b32_e32 v0, v111, v0, vcc
	v_and_b32_e32 v0, 1, v0
	s_waitcnt lgkmcnt(0)
	v_max_f32_e32 v110, v110, v110
	v_max_f32_e32 v108, v108, v110
	v_cmp_eq_u32_e64 s[2:3], 0, v0
	s_nop 1
	v_cndmask_b32_e64 v0, v108, v196, s[2:3]
	v_max_f32_e32 v116, v117, v0
	v_sub_f32_e32 v0, v117, v116
	v_exp_f32_e32 v108, v0
	s_nop 0
	v_cmp_neq_f32_e32 vcc, 1.0, v108
	s_cbranch_vccz .LBB0_1173
	v_pk_mul_f32 v[32:33], v[32:33], v[108:109] op_sel_hi:[1,0]
	v_pk_mul_f32 v[30:31], v[30:31], v[108:109] op_sel_hi:[1,0]
	v_pk_mul_f32 v[28:29], v[28:29], v[108:109] op_sel_hi:[1,0]
	v_pk_mul_f32 v[26:27], v[26:27], v[108:109] op_sel_hi:[1,0]
	v_pk_mul_f32 v[24:25], v[24:25], v[108:109] op_sel_hi:[1,0]
	v_pk_mul_f32 v[22:23], v[22:23], v[108:109] op_sel_hi:[1,0]
	v_pk_mul_f32 v[20:21], v[20:21], v[108:109] op_sel_hi:[1,0]
	v_pk_mul_f32 v[18:19], v[18:19], v[108:109] op_sel_hi:[1,0]
	v_pk_mul_f32 v[16:17], v[16:17], v[108:109] op_sel_hi:[1,0]
	v_pk_mul_f32 v[14:15], v[14:15], v[108:109] op_sel_hi:[1,0]
	v_pk_mul_f32 v[12:13], v[12:13], v[108:109] op_sel_hi:[1,0]
	v_pk_mul_f32 v[10:11], v[10:11], v[108:109] op_sel_hi:[1,0]
	v_pk_mul_f32 v[8:9], v[8:9], v[108:109] op_sel_hi:[1,0]
	v_pk_mul_f32 v[6:7], v[6:7], v[108:109] op_sel_hi:[1,0]
	v_pk_mul_f32 v[4:5], v[4:5], v[108:109] op_sel_hi:[1,0]
	v_pk_mul_f32 v[2:3], v[2:3], v[108:109] op_sel_hi:[1,0]
.LBB0_1173:
	v_max_f32_e32 v0, 0xefa18f08, v116
	v_cndmask_b32_e64 v117, v0, v198, s[2:3]
	v_sub_f32_e32 v0, v66, v117
	v_exp_f32_e32 v66, v0
	v_sub_f32_e32 v0, v82, v117
	v_exp_f32_e32 v82, v0
	v_sub_f32_e32 v0, v67, v117
	v_exp_f32_e32 v154, v0
	v_sub_f32_e32 v0, v83, v117
	v_exp_f32_e32 v0, v0
	v_sub_f32_e32 v67, v68, v117
	v_add_f32_e32 v155, v66, v82
	v_exp_f32_e32 v68, v67
	v_sub_f32_e32 v67, v84, v117
	v_pk_add_f32 v[110:111], v[154:155], v[0:1]
	v_exp_f32_e32 v84, v67
	v_sub_f32_e32 v67, v69, v117
	v_pk_add_f32 v[110:111], v[110:111], v[110:111] op_sel_hi:[0,1]
	v_exp_f32_e32 v156, v67
	v_sub_f32_e32 v67, v85, v117
	v_exp_f32_e32 v110, v67
	v_sub_f32_e32 v69, v70, v117
	v_add_f32_e32 v157, v68, v84
	v_exp_f32_e32 v70, v69
	v_sub_f32_e32 v69, v86, v117
	v_pk_add_f32 v[118:119], v[156:157], v[110:111]
	v_exp_f32_e32 v86, v69
	v_sub_f32_e32 v69, v71, v117
	v_pk_add_f32 v[158:159], v[118:119], v[118:119] op_sel_hi:[0,1]
	v_exp_f32_e32 v160, v69
	v_sub_f32_e32 v69, v87, v117
	v_exp_f32_e32 v158, v69
	v_sub_f32_e32 v69, v72, v117
	v_add_f32_e32 v161, v70, v86
	v_exp_f32_e32 v72, v69
	v_sub_f32_e32 v69, v88, v117
	v_pk_add_f32 v[126:127], v[160:161], v[158:159]
	v_exp_f32_e32 v88, v69
	v_sub_f32_e32 v69, v73, v117
	v_pk_add_f32 v[186:187], v[126:127], v[126:127] op_sel_hi:[0,1]
	v_exp_f32_e32 v188, v69
	v_sub_f32_e32 v69, v89, v117
	v_exp_f32_e32 v186, v69
	v_sub_f32_e32 v69, v74, v117
	v_add_f32_e32 v189, v72, v88
	v_exp_f32_e32 v74, v69
	v_sub_f32_e32 v69, v90, v117
	v_pk_add_f32 v[134:135], v[188:189], v[186:187]
	v_exp_f32_e32 v90, v69
	v_sub_f32_e32 v69, v75, v117
	v_pk_add_f32 v[190:191], v[134:135], v[134:135] op_sel_hi:[0,1]
	v_exp_f32_e32 v192, v69
	v_sub_f32_e32 v69, v91, v117
	v_exp_f32_e32 v190, v69
	v_sub_f32_e32 v69, v76, v117
	v_add_f32_e32 v193, v74, v90
	v_exp_f32_e32 v76, v69
	v_sub_f32_e32 v69, v92, v117
	v_pk_add_f32 v[142:143], v[192:193], v[190:191]
	v_exp_f32_e32 v92, v69
	v_sub_f32_e32 v69, v77, v117
	v_pk_add_f32 v[194:195], v[142:143], v[142:143] op_sel_hi:[0,1]
	v_exp_f32_e32 v224, v69
	v_sub_f32_e32 v69, v93, v117
	v_exp_f32_e32 v194, v69
	v_lshl_add_u32 v67, s46, 14, v112
	ds_read_b64_tr_b16 v[118:119], v67 offset:8192
	ds_read_b64_tr_b16 v[120:121], v67 offset:8704
	ds_read_b64_tr_b16 v[122:123], v67 offset:9216
	ds_read_b64_tr_b16 v[124:125], v67 offset:9728
	ds_read_b64_tr_b16 v[126:127], v67 offset:12288
	ds_read_b64_tr_b16 v[128:129], v67 offset:12800
	ds_read_b64_tr_b16 v[130:131], v67 offset:13312
	ds_read_b64_tr_b16 v[132:133], v67 offset:13824
	ds_read_b64_tr_b16 v[134:135], v67 offset:10240
	ds_read_b64_tr_b16 v[136:137], v67 offset:10752
	ds_read_b64_tr_b16 v[138:139], v67 offset:11264
	ds_read_b64_tr_b16 v[140:141], v67 offset:11776
	ds_read_b64_tr_b16 v[142:143], v67 offset:14336
	ds_read_b64_tr_b16 v[144:145], v67 offset:14848
	ds_read_b64_tr_b16 v[146:147], v67 offset:15360
	ds_read_b64_tr_b16 v[148:149], v67 offset:15872
	v_add_f32_e32 v225, v76, v92
	v_sub_f32_e32 v67, v78, v117
	v_pk_add_f32 v[150:151], v[224:225], v[194:195]
	v_exp_f32_e32 v78, v67
	v_sub_f32_e32 v67, v94, v117
	v_pk_add_f32 v[226:227], v[150:151], v[150:151] op_sel_hi:[0,1]
	v_cvt_pk_bf16_f32 v150, v66, v154
	v_cvt_pk_bf16_f32 v151, v68, v156
	v_cvt_pk_bf16_f32 v152, v70, v160
	v_cvt_pk_bf16_f32 v153, v72, v188
	v_exp_f32_e32 v94, v67
	v_sub_f32_e32 v67, v79, v117
	s_waitcnt lgkmcnt(0)
	v_mfma_f32_32x32x16_bf16 v[2:17], v[118:121], v[150:153], v[2:17]
	v_exp_f32_e32 v228, v67
	v_sub_f32_e32 v67, v95, v117
	v_exp_f32_e32 v226, v67
	v_sub_f32_e32 v67, v80, v117
	v_exp_f32_e32 v80, v67
	v_sub_f32_e32 v67, v81, v117
	v_exp_f32_e32 v81, v67
	v_mfma_f32_32x32x16_bf16 v[18:33], v[126:129], v[150:153], v[18:33]
	v_cvt_pk_bf16_f32 v118, v74, v192
	v_cvt_pk_bf16_f32 v119, v76, v224
	v_cvt_pk_bf16_f32 v120, v78, v228
	v_cvt_pk_bf16_f32 v121, v80, v81
	v_sub_f32_e32 v67, v96, v117
	v_exp_f32_e32 v96, v67
	v_sub_f32_e32 v67, v97, v117
	v_mfma_f32_32x32x16_bf16 v[2:17], v[122:125], v[118:121], v[2:17]
	v_exp_f32_e32 v97, v67
	v_add_f32_e32 v229, v78, v94
	v_pk_add_f32 v[122:123], v[228:229], v[226:227]
	v_add_f32_e32 v111, v80, v96
	v_pk_add_f32 v[122:123], v[122:123], v[122:123] op_sel_hi:[0,1]
	v_mov_b32_e32 v122, v97
	v_mfma_f32_32x32x16_bf16 v[18:33], v[130:133], v[118:121], v[18:33]
	v_cvt_pk_bf16_f32 v118, v82, v0
	v_cvt_pk_bf16_f32 v119, v84, v110
	v_cvt_pk_bf16_f32 v120, v86, v158
	v_cvt_pk_bf16_f32 v121, v88, v186
	v_mov_b32_e32 v110, v81
	v_pk_add_f32 v[110:111], v[110:111], v[122:123]
	v_mfma_f32_32x32x16_bf16 v[2:17], v[134:137], v[118:121], v[2:17]
	v_add_f32_e32 v0, v110, v111
	v_fmac_f32_e32 v0, v115, v108
	v_mfma_f32_32x32x16_bf16 v[18:33], v[142:145], v[118:121], v[18:33]
	v_cvt_pk_bf16_f32 v118, v90, v190
	v_cvt_pk_bf16_f32 v119, v92, v194
	v_cvt_pk_bf16_f32 v120, v94, v226
	v_cvt_pk_bf16_f32 v121, v96, v97
	s_nop 1
	v_mfma_f32_32x32x16_bf16 v[2:17], v[138:141], v[118:121], v[2:17]
	v_mov_b32_e32 v115, v0
	v_mfma_f32_32x32x16_bf16 v[18:33], v[146:149], v[118:121], v[18:33]
	s_branch .LBB0_1175

.LBB0_1188:
	v_max3_f32 v0, v34, v35, v36
	v_max3_f32 v0, v0, v37, v38
	v_max3_f32 v0, v0, v39, v40
	v_max3_f32 v0, v0, v41, v42
	v_max3_f32 v0, v0, v43, v44
	v_max3_f32 v0, v0, v45, v46
	v_max3_f32 v0, v0, v47, v48
	v_max3_f32 v0, v0, v49, v50
	v_max3_f32 v0, v0, v51, v52
	v_max3_f32 v0, v0, v53, v54
	v_max3_f32 v0, v0, v55, v56
	v_max3_f32 v0, v0, v57, v58
	v_max3_f32 v0, v0, v59, v60
	v_max3_f32 v0, v0, v61, v62
	v_max3_f32 v0, v0, v63, v64
	v_max_f32_e32 v0, v0, v65
	ds_bpermute_b32 v102, v209, v0
	s_waitcnt lgkmcnt(0)
	v_max3_f32 v108, v107, v0, v102
	v_sub_f32_e32 v0, v107, v108
	v_exp_f32_e32 v102, v0
	s_nop 0
	v_cmp_neq_f32_e32 vcc, 1.0, v102
	s_cbranch_vccz .LBB0_1190
	v_pk_mul_f32 v[16:17], v[16:17], v[102:103] op_sel_hi:[1,0]
	v_pk_mul_f32 v[14:15], v[14:15], v[102:103] op_sel_hi:[1,0]
	v_pk_mul_f32 v[12:13], v[12:13], v[102:103] op_sel_hi:[1,0]
	v_pk_mul_f32 v[10:11], v[10:11], v[102:103] op_sel_hi:[1,0]
	v_pk_mul_f32 v[8:9], v[8:9], v[102:103] op_sel_hi:[1,0]
	v_pk_mul_f32 v[6:7], v[6:7], v[102:103] op_sel_hi:[1,0]
	v_pk_mul_f32 v[4:5], v[4:5], v[102:103] op_sel_hi:[1,0]
	v_pk_mul_f32 v[2:3], v[2:3], v[102:103] op_sel_hi:[1,0]
	v_pk_mul_f32 v[32:33], v[32:33], v[102:103] op_sel_hi:[1,0]
	v_pk_mul_f32 v[30:31], v[30:31], v[102:103] op_sel_hi:[1,0]
	v_pk_mul_f32 v[28:29], v[28:29], v[102:103] op_sel_hi:[1,0]
	v_pk_mul_f32 v[26:27], v[26:27], v[102:103] op_sel_hi:[1,0]
	v_pk_mul_f32 v[24:25], v[24:25], v[102:103] op_sel_hi:[1,0]
	v_pk_mul_f32 v[22:23], v[22:23], v[102:103] op_sel_hi:[1,0]
	v_pk_mul_f32 v[20:21], v[20:21], v[102:103] op_sel_hi:[1,0]
	v_pk_mul_f32 v[18:19], v[18:19], v[102:103] op_sel_hi:[1,0]
.LBB0_1190:
	v_max_f32_e32 v107, 0xefa18f08, v108
	v_sub_f32_e32 v0, v34, v107
	v_exp_f32_e32 v34, v0
	v_sub_f32_e32 v0, v50, v107
	v_exp_f32_e32 v50, v0
	v_sub_f32_e32 v0, v35, v107
	v_exp_f32_e32 v110, v0
	v_sub_f32_e32 v0, v51, v107
	v_exp_f32_e32 v0, v0
	v_sub_f32_e32 v35, v36, v107
	v_add_f32_e32 v111, v34, v50
	v_exp_f32_e32 v36, v35
	v_sub_f32_e32 v35, v52, v107
	v_pk_add_f32 v[104:105], v[110:111], v[0:1]
	v_exp_f32_e32 v52, v35
	v_sub_f32_e32 v35, v37, v107
	v_pk_add_f32 v[104:105], v[104:105], v[104:105] op_sel_hi:[0,1]
	v_exp_f32_e32 v150, v35
	v_sub_f32_e32 v35, v53, v107
	v_exp_f32_e32 v104, v35
	v_sub_f32_e32 v37, v38, v107
	v_add_f32_e32 v151, v36, v52
	v_exp_f32_e32 v38, v37
	v_sub_f32_e32 v37, v54, v107
	v_pk_add_f32 v[114:115], v[150:151], v[104:105]
	v_exp_f32_e32 v54, v37
	v_sub_f32_e32 v37, v39, v107
	v_pk_add_f32 v[152:153], v[114:115], v[114:115] op_sel_hi:[0,1]
	v_exp_f32_e32 v154, v37
	v_sub_f32_e32 v37, v55, v107
	v_exp_f32_e32 v152, v37
	v_sub_f32_e32 v37, v40, v107
	v_add_f32_e32 v155, v38, v54
	v_exp_f32_e32 v40, v37
	v_sub_f32_e32 v37, v56, v107
	v_pk_add_f32 v[122:123], v[154:155], v[152:153]
	v_exp_f32_e32 v56, v37
	v_sub_f32_e32 v37, v41, v107
	v_pk_add_f32 v[156:157], v[122:123], v[122:123] op_sel_hi:[0,1]
	v_exp_f32_e32 v158, v37
	v_sub_f32_e32 v37, v57, v107
	v_exp_f32_e32 v156, v37
	v_sub_f32_e32 v37, v42, v107
	v_add_f32_e32 v159, v40, v56
	v_exp_f32_e32 v42, v37
	v_sub_f32_e32 v37, v58, v107
	v_pk_add_f32 v[130:131], v[158:159], v[156:157]
	v_exp_f32_e32 v58, v37
	v_sub_f32_e32 v37, v43, v107
	v_pk_add_f32 v[160:161], v[130:131], v[130:131] op_sel_hi:[0,1]
	v_exp_f32_e32 v186, v37
	v_sub_f32_e32 v37, v59, v107
	v_exp_f32_e32 v160, v37
	v_sub_f32_e32 v37, v44, v107
	v_add_f32_e32 v187, v42, v58
	v_exp_f32_e32 v44, v37
	v_sub_f32_e32 v37, v60, v107
	v_pk_add_f32 v[138:139], v[186:187], v[160:161]
	v_exp_f32_e32 v60, v37
	v_sub_f32_e32 v37, v45, v107
	v_pk_add_f32 v[188:189], v[138:139], v[138:139] op_sel_hi:[0,1]
	v_exp_f32_e32 v190, v37
	v_sub_f32_e32 v37, v61, v107
	v_exp_f32_e32 v188, v37
	v_lshl_add_u32 v35, s44, 14, v112
	ds_read_b64_tr_b16 v[114:115], v35 offset:8192
	ds_read_b64_tr_b16 v[116:117], v35 offset:8704
	ds_read_b64_tr_b16 v[118:119], v35 offset:9216
	ds_read_b64_tr_b16 v[120:121], v35 offset:9728
	ds_read_b64_tr_b16 v[122:123], v35 offset:12288
	ds_read_b64_tr_b16 v[124:125], v35 offset:12800
	ds_read_b64_tr_b16 v[126:127], v35 offset:13312
	ds_read_b64_tr_b16 v[128:129], v35 offset:13824
	ds_read_b64_tr_b16 v[130:131], v35 offset:10240
	ds_read_b64_tr_b16 v[132:133], v35 offset:10752
	ds_read_b64_tr_b16 v[134:135], v35 offset:11264
	ds_read_b64_tr_b16 v[136:137], v35 offset:11776
	ds_read_b64_tr_b16 v[138:139], v35 offset:14336
	ds_read_b64_tr_b16 v[140:141], v35 offset:14848
	ds_read_b64_tr_b16 v[142:143], v35 offset:15360
	ds_read_b64_tr_b16 v[144:145], v35 offset:15872
	v_add_f32_e32 v191, v44, v60
	v_sub_f32_e32 v35, v46, v107
	v_pk_add_f32 v[146:147], v[190:191], v[188:189]
	v_exp_f32_e32 v46, v35
	v_sub_f32_e32 v35, v62, v107
	v_pk_add_f32 v[192:193], v[146:147], v[146:147] op_sel_hi:[0,1]
	v_cvt_pk_bf16_f32 v146, v34, v110
	v_cvt_pk_bf16_f32 v147, v36, v150
	v_cvt_pk_bf16_f32 v148, v38, v154
	v_cvt_pk_bf16_f32 v149, v40, v158
	v_exp_f32_e32 v62, v35
	v_sub_f32_e32 v35, v47, v107
	s_waitcnt lgkmcnt(0)
	v_mfma_f32_32x32x16_bf16 v[18:33], v[114:117], v[146:149], v[18:33]
	v_exp_f32_e32 v194, v35
	v_sub_f32_e32 v35, v63, v107
	v_exp_f32_e32 v192, v35
	v_sub_f32_e32 v35, v48, v107
	v_exp_f32_e32 v48, v35
	v_sub_f32_e32 v35, v49, v107
	v_exp_f32_e32 v49, v35
	v_mfma_f32_32x32x16_bf16 v[2:17], v[122:125], v[146:149], v[2:17]
	v_cvt_pk_bf16_f32 v114, v42, v186
	v_cvt_pk_bf16_f32 v115, v44, v190
	v_cvt_pk_bf16_f32 v116, v46, v194
	v_cvt_pk_bf16_f32 v117, v48, v49
	v_sub_f32_e32 v35, v64, v107
	v_exp_f32_e32 v64, v35
	v_sub_f32_e32 v35, v65, v107
	v_mfma_f32_32x32x16_bf16 v[18:33], v[118:121], v[114:117], v[18:33]
	v_exp_f32_e32 v65, v35
	v_add_f32_e32 v195, v46, v62
	v_pk_add_f32 v[118:119], v[194:195], v[192:193]
	v_add_f32_e32 v105, v48, v64
	v_pk_add_f32 v[118:119], v[118:119], v[118:119] op_sel_hi:[0,1]
	v_mov_b32_e32 v118, v65
	v_mfma_f32_32x32x16_bf16 v[2:17], v[126:129], v[114:117], v[2:17]
	v_cvt_pk_bf16_f32 v114, v50, v0
	v_cvt_pk_bf16_f32 v115, v52, v104
	v_cvt_pk_bf16_f32 v116, v54, v152
	v_cvt_pk_bf16_f32 v117, v56, v156
	v_mov_b32_e32 v104, v49
	v_pk_add_f32 v[104:105], v[104:105], v[118:119]
	v_mfma_f32_32x32x16_bf16 v[18:33], v[130:133], v[114:117], v[18:33]
	v_add_f32_e32 v0, v104, v105
	v_fmac_f32_e32 v0, v106, v102
	v_mfma_f32_32x32x16_bf16 v[2:17], v[138:141], v[114:117], v[2:17]
	v_cvt_pk_bf16_f32 v114, v58, v160
	v_cvt_pk_bf16_f32 v115, v60, v188
	v_cvt_pk_bf16_f32 v116, v62, v192
	v_cvt_pk_bf16_f32 v117, v64, v65
	s_nop 1
	v_mfma_f32_32x32x16_bf16 v[18:33], v[134:137], v[114:117], v[18:33]
	v_mov_b32_e32 v106, v0
	v_mfma_f32_32x32x16_bf16 v[2:17], v[142:145], v[114:117], v[2:17]
	s_branch .LBB0_1192

.LBB0_1199:
	v_max3_f32 v0, v66, v67, v68
	v_max3_f32 v0, v0, v69, v70
	v_max3_f32 v0, v0, v71, v72
	v_max3_f32 v0, v0, v73, v74
	v_max3_f32 v0, v0, v75, v76
	v_max3_f32 v0, v0, v77, v78
	v_max3_f32 v0, v0, v79, v80
	v_max3_f32 v0, v0, v81, v82
	v_max3_f32 v0, v0, v83, v84
	v_max3_f32 v0, v0, v85, v86
	v_max3_f32 v0, v0, v87, v88
	v_max3_f32 v0, v0, v89, v90
	v_max3_f32 v0, v0, v91, v92
	v_max3_f32 v0, v0, v93, v94
	v_max3_f32 v0, v0, v95, v96
	v_max_f32_e32 v0, v0, v97
	ds_bpermute_b32 v102, v209, v0
	s_waitcnt lgkmcnt(0)
	v_max3_f32 v107, v108, v0, v102
	v_sub_f32_e32 v0, v108, v107
	v_exp_f32_e32 v102, v0
	s_nop 0
	v_cmp_neq_f32_e32 vcc, 1.0, v102
	s_cbranch_vccz .LBB0_1201
	v_pk_mul_f32 v[16:17], v[16:17], v[102:103] op_sel_hi:[1,0]
	v_pk_mul_f32 v[14:15], v[14:15], v[102:103] op_sel_hi:[1,0]
	v_pk_mul_f32 v[12:13], v[12:13], v[102:103] op_sel_hi:[1,0]
	v_pk_mul_f32 v[10:11], v[10:11], v[102:103] op_sel_hi:[1,0]
	v_pk_mul_f32 v[8:9], v[8:9], v[102:103] op_sel_hi:[1,0]
	v_pk_mul_f32 v[6:7], v[6:7], v[102:103] op_sel_hi:[1,0]
	v_pk_mul_f32 v[4:5], v[4:5], v[102:103] op_sel_hi:[1,0]
	v_pk_mul_f32 v[2:3], v[2:3], v[102:103] op_sel_hi:[1,0]
	v_pk_mul_f32 v[32:33], v[32:33], v[102:103] op_sel_hi:[1,0]
	v_pk_mul_f32 v[30:31], v[30:31], v[102:103] op_sel_hi:[1,0]
	v_pk_mul_f32 v[28:29], v[28:29], v[102:103] op_sel_hi:[1,0]
	v_pk_mul_f32 v[26:27], v[26:27], v[102:103] op_sel_hi:[1,0]
	v_pk_mul_f32 v[24:25], v[24:25], v[102:103] op_sel_hi:[1,0]
	v_pk_mul_f32 v[22:23], v[22:23], v[102:103] op_sel_hi:[1,0]
	v_pk_mul_f32 v[20:21], v[20:21], v[102:103] op_sel_hi:[1,0]
	v_pk_mul_f32 v[18:19], v[18:19], v[102:103] op_sel_hi:[1,0]
.LBB0_1201:
	v_max_f32_e32 v108, 0xefa18f08, v107
	v_sub_f32_e32 v0, v66, v108
	v_exp_f32_e32 v66, v0
	v_sub_f32_e32 v0, v82, v108
	v_exp_f32_e32 v82, v0
	v_sub_f32_e32 v0, v67, v108
	v_exp_f32_e32 v110, v0
	v_sub_f32_e32 v0, v83, v108
	v_exp_f32_e32 v0, v0
	v_sub_f32_e32 v67, v68, v108
	v_add_f32_e32 v111, v66, v82
	v_exp_f32_e32 v68, v67
	v_sub_f32_e32 v67, v84, v108
	v_pk_add_f32 v[104:105], v[110:111], v[0:1]
	v_exp_f32_e32 v84, v67
	v_sub_f32_e32 v67, v69, v108
	v_pk_add_f32 v[104:105], v[104:105], v[104:105] op_sel_hi:[0,1]
	v_exp_f32_e32 v150, v67
	v_sub_f32_e32 v67, v85, v108
	v_exp_f32_e32 v104, v67
	v_sub_f32_e32 v69, v70, v108
	v_add_f32_e32 v151, v68, v84
	v_exp_f32_e32 v70, v69
	v_sub_f32_e32 v69, v86, v108
	v_pk_add_f32 v[114:115], v[150:151], v[104:105]
	v_exp_f32_e32 v86, v69
	v_sub_f32_e32 v69, v71, v108
	v_pk_add_f32 v[152:153], v[114:115], v[114:115] op_sel_hi:[0,1]
	v_exp_f32_e32 v154, v69
	v_sub_f32_e32 v69, v87, v108
	v_exp_f32_e32 v152, v69
	v_sub_f32_e32 v69, v72, v108
	v_add_f32_e32 v155, v70, v86
	v_exp_f32_e32 v72, v69
	v_sub_f32_e32 v69, v88, v108
	v_pk_add_f32 v[122:123], v[154:155], v[152:153]
	v_exp_f32_e32 v88, v69
	v_sub_f32_e32 v69, v73, v108
	v_pk_add_f32 v[156:157], v[122:123], v[122:123] op_sel_hi:[0,1]
	v_exp_f32_e32 v158, v69
	v_sub_f32_e32 v69, v89, v108
	v_exp_f32_e32 v156, v69
	v_sub_f32_e32 v69, v74, v108
	v_add_f32_e32 v159, v72, v88
	v_exp_f32_e32 v74, v69
	v_sub_f32_e32 v69, v90, v108
	v_pk_add_f32 v[130:131], v[158:159], v[156:157]
	v_exp_f32_e32 v90, v69
	v_sub_f32_e32 v69, v75, v108
	v_pk_add_f32 v[160:161], v[130:131], v[130:131] op_sel_hi:[0,1]
	v_exp_f32_e32 v186, v69
	v_sub_f32_e32 v69, v91, v108
	v_exp_f32_e32 v160, v69
	v_sub_f32_e32 v69, v76, v108
	v_add_f32_e32 v187, v74, v90
	v_exp_f32_e32 v76, v69
	v_sub_f32_e32 v69, v92, v108
	v_pk_add_f32 v[138:139], v[186:187], v[160:161]
	v_exp_f32_e32 v92, v69
	v_sub_f32_e32 v69, v77, v108
	v_pk_add_f32 v[188:189], v[138:139], v[138:139] op_sel_hi:[0,1]
	v_exp_f32_e32 v190, v69
	v_sub_f32_e32 v69, v93, v108
	v_exp_f32_e32 v188, v69
	v_lshl_add_u32 v67, s45, 14, v112
	ds_read_b64_tr_b16 v[114:115], v67 offset:8192
	ds_read_b64_tr_b16 v[116:117], v67 offset:8704
	ds_read_b64_tr_b16 v[118:119], v67 offset:9216
	ds_read_b64_tr_b16 v[120:121], v67 offset:9728
	ds_read_b64_tr_b16 v[122:123], v67 offset:12288
	ds_read_b64_tr_b16 v[124:125], v67 offset:12800
	ds_read_b64_tr_b16 v[126:127], v67 offset:13312
	ds_read_b64_tr_b16 v[128:129], v67 offset:13824
	ds_read_b64_tr_b16 v[130:131], v67 offset:10240
	ds_read_b64_tr_b16 v[132:133], v67 offset:10752
	ds_read_b64_tr_b16 v[134:135], v67 offset:11264
	ds_read_b64_tr_b16 v[136:137], v67 offset:11776
	ds_read_b64_tr_b16 v[138:139], v67 offset:14336
	ds_read_b64_tr_b16 v[140:141], v67 offset:14848
	ds_read_b64_tr_b16 v[142:143], v67 offset:15360
	ds_read_b64_tr_b16 v[144:145], v67 offset:15872
	v_add_f32_e32 v191, v76, v92
	v_sub_f32_e32 v67, v78, v108
	v_pk_add_f32 v[146:147], v[190:191], v[188:189]
	v_exp_f32_e32 v78, v67
	v_sub_f32_e32 v67, v94, v108
	v_pk_add_f32 v[192:193], v[146:147], v[146:147] op_sel_hi:[0,1]
	v_cvt_pk_bf16_f32 v146, v66, v110
	v_cvt_pk_bf16_f32 v147, v68, v150
	v_cvt_pk_bf16_f32 v148, v70, v154
	v_cvt_pk_bf16_f32 v149, v72, v158
	v_exp_f32_e32 v94, v67
	v_sub_f32_e32 v67, v79, v108
	s_waitcnt lgkmcnt(0)
	v_mfma_f32_32x32x16_bf16 v[18:33], v[114:117], v[146:149], v[18:33]
	v_exp_f32_e32 v194, v67
	v_sub_f32_e32 v67, v95, v108
	v_exp_f32_e32 v192, v67
	v_sub_f32_e32 v67, v80, v108
	v_exp_f32_e32 v80, v67
	v_sub_f32_e32 v67, v81, v108
	v_exp_f32_e32 v81, v67
	v_mfma_f32_32x32x16_bf16 v[2:17], v[122:125], v[146:149], v[2:17]
	v_cvt_pk_bf16_f32 v114, v74, v186
	v_cvt_pk_bf16_f32 v115, v76, v190
	v_cvt_pk_bf16_f32 v116, v78, v194
	v_cvt_pk_bf16_f32 v117, v80, v81
	v_sub_f32_e32 v67, v96, v108
	v_exp_f32_e32 v96, v67
	v_sub_f32_e32 v67, v97, v108
	v_mfma_f32_32x32x16_bf16 v[18:33], v[118:121], v[114:117], v[18:33]
	v_exp_f32_e32 v97, v67
	v_add_f32_e32 v195, v78, v94
	v_pk_add_f32 v[118:119], v[194:195], v[192:193]
	v_add_f32_e32 v105, v80, v96
	v_pk_add_f32 v[118:119], v[118:119], v[118:119] op_sel_hi:[0,1]
	v_mov_b32_e32 v118, v97
	v_mfma_f32_32x32x16_bf16 v[2:17], v[126:129], v[114:117], v[2:17]
	v_cvt_pk_bf16_f32 v114, v82, v0
	v_cvt_pk_bf16_f32 v115, v84, v104
	v_cvt_pk_bf16_f32 v116, v86, v152
	v_cvt_pk_bf16_f32 v117, v88, v156
	v_mov_b32_e32 v104, v81
	v_pk_add_f32 v[104:105], v[104:105], v[118:119]
	v_mfma_f32_32x32x16_bf16 v[18:33], v[130:133], v[114:117], v[18:33]
	v_add_f32_e32 v0, v104, v105
	s_add_i32 s0, s43, 1
	v_fmac_f32_e32 v0, v106, v102
	s_cmp_lg_u32 s43, 5
	v_mfma_f32_32x32x16_bf16 v[2:17], v[138:141], v[114:117], v[2:17]
	v_cvt_pk_bf16_f32 v114, v90, v160
	v_cvt_pk_bf16_f32 v115, v92, v188
	v_cvt_pk_bf16_f32 v116, v94, v192
	v_cvt_pk_bf16_f32 v117, v96, v97
	s_nop 1
	v_mfma_f32_32x32x16_bf16 v[18:33], v[134:137], v[114:117], v[18:33]
	s_cselect_b32 s43, s0, 0
	v_mfma_f32_32x32x16_bf16 v[2:17], v[142:145], v[114:117], v[2:17]
	v_mov_b32_e32 v106, v0
	s_branch .LBB0_1180
